# v074 plus SwiGLU epilogue (P8, P14): (1+e)/r^2 FMA and the final product done two outputs at a time with v_pk_fma_f32 / v_pk_mul_f32 (27 -> 23 instructions per 4 outputs)
# speedup vs baseline: 1.0015x; 1.0015x over previous
; __device__ __forceinline__ unsigned cvt_pk_bf16(float lo, float hi) { return pk_bf16(lo, hi); }
; __device__ __forceinline__ float silu_f(float x) { return x * __builtin_amdgcn_rcpf(1.f + __builtin_amdgcn_exp2f(-x * L2E)); }
;     __device__ __forceinline__ void operator()(const f32x4 (&acc)[2][2][4][2], const Unit& u, int wr, int wc, int fr, int fq) const {
;         EPI_ROWS_BEGIN
;             const int hc = (u.pn * BM + colt) >> 1; const float r = 1.f / sqrtf(rstd[row] * (1.f / DM) + RMS_EPS);
;             const float h0 = silu_f(v0[0] * r) * (v0[1] * r), h1 = silu_f(v0[2] * r) * (v0[3] * r), h2 = silu_f(v1[0] * r) * (v1[1] * r), h3 = silu_f(v1[2] * r) * (v1[3] * r);
;             u32x2 w; w.x = cvt_pk_bf16(h0, h1); w.y = cvt_pk_bf16(h2, h3);
;             *(u32x2*)(hid + (size_t)row * HIDLD + hc) = w;
.LBB0_1052:
	v_mov_b32_e32 v230, v238
	v_mov_b32_e32 v231, v239
	v_mov_b32_e32 v232, v240
	v_mov_b32_e32 v233, v241
	v_mov_b32_e32 v234, v242
	v_mov_b32_e32 v235, v243
	v_mov_b32_e32 v236, v244
	v_mov_b32_e32 v237, v245
	v_lshl_add_u32 v246, s18, 8, v146
	v_mov_b32_e32 v247, 0
	v_lshl_add_u64 v[246:247], v[246:247], 2, s[12:13]
	global_load_dword v238, v[246:247], off
	global_load_dword v239, v[246:247], off offset:64
	global_load_dword v240, v[246:247], off offset:128
	global_load_dword v241, v[246:247], off offset:192
	global_load_dword v242, v[246:247], off offset:512
	global_load_dword v243, v[246:247], off offset:576
	global_load_dword v244, v[246:247], off offset:640
	global_load_dword v245, v[246:247], off offset:704
	v_lshl_add_u32 v144, s0, 8, v146
	s_mov_b32 s98, 0x16800
	s_mov_b32 s99, 0
	v_mov_b64_e32 v[212:213], s[10:11]
	v_lshl_or_b32 v214, s56, 8, v148
	v_mov_b32_e32 v215, 0
	v_mad_u64_u32 v[196:197], vcc, v144, s54, v[212:213]
	v_lshl_add_u64 v[196:197], v[196:197], 0, v[214:215]
	v_lshl_add_u64 v[198:199], v[196:197], 0, s[98:99]
	v_lshl_add_u64 v[204:205], s[98:99], 3, v[196:197]
	v_lshl_add_u64 v[200:201], v[198:199], 0, s[98:99]
	v_lshl_add_u64 v[206:207], v[204:205], 0, s[98:99]
	v_lshl_add_u64 v[202:203], v[200:201], 0, s[98:99]
	v_lshl_add_u64 v[208:209], v[206:207], 0, s[98:99]
	v_lshl_add_u64 v[210:211], v[208:209], 0, s[98:99]
	v_fmamk_f32 v230, v230, 0x3a800000, v152
	v_fmamk_f32 v231, v231, 0x3a800000, v152
	v_fmamk_f32 v232, v232, 0x3a800000, v152
	v_fmamk_f32 v233, v233, 0x3a800000, v152
	v_fmamk_f32 v234, v234, 0x3a800000, v152
	v_fmamk_f32 v235, v235, 0x3a800000, v152
	v_fmamk_f32 v236, v236, 0x3a800000, v152
	v_fmamk_f32 v237, v237, 0x3a800000, v152
	v_rsq_f32_e32 v164, v230
	v_rsq_f32_e32 v165, v231
	v_rsq_f32_e32 v166, v232
	v_rsq_f32_e32 v167, v233
	v_rsq_f32_e32 v168, v234
	v_rsq_f32_e32 v169, v235
	v_rsq_f32_e32 v170, v236
	v_rsq_f32_e32 v171, v237
	v_mul_f32_e32 v172, v230, v164
	v_mul_f32_e32 v173, v231, v165
	v_mul_f32_e32 v174, v232, v166
	v_mul_f32_e32 v175, v233, v167
	v_mul_f32_e32 v176, v234, v168
	v_mul_f32_e32 v177, v235, v169
	v_mul_f32_e32 v178, v236, v170
	v_mul_f32_e32 v179, v237, v171
	v_fma_f32 v172, -v172, v164, 1.0
	v_fma_f32 v173, -v173, v165, 1.0
	v_fma_f32 v174, -v174, v166, 1.0
	v_fma_f32 v175, -v175, v167, 1.0
	v_fma_f32 v176, -v176, v168, 1.0
	v_fma_f32 v177, -v177, v169, 1.0
	v_fma_f32 v178, -v178, v170, 1.0
	v_fma_f32 v179, -v179, v171, 1.0
	v_mul_f32_e32 v180, 0.5, v164
	v_mul_f32_e32 v181, 0.5, v165
	v_mul_f32_e32 v182, 0.5, v166
	v_mul_f32_e32 v183, 0.5, v167
	v_mul_f32_e32 v184, 0.5, v168
	v_mul_f32_e32 v185, 0.5, v169
	v_mul_f32_e32 v186, 0.5, v170
	v_mul_f32_e32 v187, 0.5, v171
	v_fma_f32 v164, v180, v172, v164
	v_fma_f32 v165, v181, v173, v165
	v_fma_f32 v166, v182, v174, v166
	v_fma_f32 v167, v183, v175, v167
	v_fma_f32 v168, v184, v176, v168
	v_fma_f32 v169, v185, v177, v169
	v_fma_f32 v170, v186, v178, v170
	v_fma_f32 v171, v187, v179, v171
	v_mul_f32_e32 v172, 0xbfb8aa3b, v164
	v_mul_f32_e32 v173, 0xbfb8aa3b, v165
	v_mul_f32_e32 v174, 0xbfb8aa3b, v166
	v_mul_f32_e32 v175, 0xbfb8aa3b, v167
	v_mul_f32_e32 v176, 0xbfb8aa3b, v168
	v_mul_f32_e32 v177, 0xbfb8aa3b, v169
	v_mul_f32_e32 v178, 0xbfb8aa3b, v170
	v_mul_f32_e32 v179, 0xbfb8aa3b, v171
	v_mul_f32_e32 v216, v124, v172
	v_mul_f32_e32 v217, v126, v172
	v_mul_f32_e32 v218, v120, v172
	v_mul_f32_e32 v219, v122, v172
	v_mul_f32_e32 v124, v124, v125
	v_mul_f32_e32 v125, v126, v127
	v_mul_f32_e32 v126, v120, v121
	v_mul_f32_e32 v127, v122, v123
	v_exp_f32_e32 v216, v216
	v_exp_f32_e32 v217, v217
	v_exp_f32_e32 v218, v218
	v_exp_f32_e32 v219, v219
	v_pk_fma_f32 v[216:217], v[216:217], v[230:231], v[230:231] op_sel_hi:[1,0,0]
	v_pk_fma_f32 v[218:219], v[218:219], v[230:231], v[230:231] op_sel_hi:[1,0,0]
	v_rcp_f32_e32 v216, v216
	v_rcp_f32_e32 v217, v217
	v_rcp_f32_e32 v218, v218
	v_rcp_f32_e32 v219, v219
	v_pk_mul_f32 v[124:125], v[124:125], v[216:217]
	v_pk_mul_f32 v[126:127], v[126:127], v[218:219]
	v_cvt_pk_bf16_f32 v124, v124, v125
	v_cvt_pk_bf16_f32 v125, v126, v127
	global_store_dwordx2 v[196:197], v[124:125], off
	v_mul_f32_e32 v220, v116, v172
	v_mul_f32_e32 v221, v118, v172
	v_mul_f32_e32 v222, v112, v172
	v_mul_f32_e32 v223, v114, v172
	v_mul_f32_e32 v116, v116, v117
	v_mul_f32_e32 v117, v118, v119
	v_mul_f32_e32 v118, v112, v113
	v_mul_f32_e32 v119, v114, v115
	v_exp_f32_e32 v220, v220
	v_exp_f32_e32 v221, v221
	v_exp_f32_e32 v222, v222
	v_exp_f32_e32 v223, v223
	v_pk_fma_f32 v[220:221], v[220:221], v[230:231], v[230:231] op_sel_hi:[1,0,0]
	v_pk_fma_f32 v[222:223], v[222:223], v[230:231], v[230:231] op_sel_hi:[1,0,0]
	v_rcp_f32_e32 v220, v220
	v_rcp_f32_e32 v221, v221
	v_rcp_f32_e32 v222, v222
	v_rcp_f32_e32 v223, v223
	v_pk_mul_f32 v[116:117], v[116:117], v[220:221]
	v_pk_mul_f32 v[118:119], v[118:119], v[222:223]
	v_cvt_pk_bf16_f32 v116, v116, v117
	v_cvt_pk_bf16_f32 v117, v118, v119
	global_store_dwordx2 v[196:197], v[116:117], off offset:128
	v_mul_f32_e32 v216, v108, v173
	v_mul_f32_e32 v217, v110, v173
	v_mul_f32_e32 v218, v104, v173
	v_mul_f32_e32 v219, v106, v173
	v_mul_f32_e32 v108, v108, v109
	v_mul_f32_e32 v109, v110, v111
	v_mul_f32_e32 v110, v104, v105
	v_mul_f32_e32 v111, v106, v107
	v_exp_f32_e32 v216, v216
	v_exp_f32_e32 v217, v217
	v_exp_f32_e32 v218, v218
	v_exp_f32_e32 v219, v219
	v_pk_fma_f32 v[216:217], v[216:217], v[230:231], v[230:231] op_sel:[0,1,1] op_sel_hi:[1,1,1]
	v_pk_fma_f32 v[218:219], v[218:219], v[230:231], v[230:231] op_sel:[0,1,1] op_sel_hi:[1,1,1]
	v_rcp_f32_e32 v216, v216
	v_rcp_f32_e32 v217, v217
	v_rcp_f32_e32 v218, v218
	v_rcp_f32_e32 v219, v219
; __device__ __forceinline__ unsigned cvt_pk_bf16(float lo, float hi) { return pk_bf16(lo, hi); }
; __device__ __forceinline__ float silu_f(float x) { return x * __builtin_amdgcn_rcpf(1.f + __builtin_amdgcn_exp2f(-x * L2E)); }
;     __device__ __forceinline__ void operator()(const f32x4 (&acc)[2][2][4][2], const Unit& u, int wr, int wc, int fr, int fq) const {
;         EPI_ROWS_BEGIN
;             const int hc = (u.pn * BM + colt) >> 1; const float r = 1.f / sqrtf(rstd[row] * (1.f / DM) + RMS_EPS);
;             const float h0 = silu_f(v0[0] * r) * (v0[1] * r), h1 = silu_f(v0[2] * r) * (v0[3] * r), h2 = silu_f(v1[0] * r) * (v1[1] * r), h3 = silu_f(v1[2] * r) * (v1[3] * r);
;             u32x2 w; w.x = cvt_pk_bf16(h0, h1); w.y = cvt_pk_bf16(h2, h3);
;             *(u32x2*)(hid + (size_t)row * HIDLD + hc) = w;
	v_pk_mul_f32 v[108:109], v[108:109], v[216:217]
	v_pk_mul_f32 v[110:111], v[110:111], v[218:219]
	v_cvt_pk_bf16_f32 v108, v108, v109
	v_cvt_pk_bf16_f32 v109, v110, v111
	global_store_dwordx2 v[198:199], v[108:109], off
	v_mul_f32_e32 v220, v100, v173
	v_mul_f32_e32 v221, v102, v173
	v_mul_f32_e32 v222, v96, v173
	v_mul_f32_e32 v223, v98, v173
	v_mul_f32_e32 v100, v100, v101
	v_mul_f32_e32 v101, v102, v103
	v_mul_f32_e32 v102, v96, v97
	v_mul_f32_e32 v103, v98, v99
	v_exp_f32_e32 v220, v220
	v_exp_f32_e32 v221, v221
	v_exp_f32_e32 v222, v222
	v_exp_f32_e32 v223, v223
	v_pk_fma_f32 v[220:221], v[220:221], v[230:231], v[230:231] op_sel:[0,1,1] op_sel_hi:[1,1,1]
	v_pk_fma_f32 v[222:223], v[222:223], v[230:231], v[230:231] op_sel:[0,1,1] op_sel_hi:[1,1,1]
	v_rcp_f32_e32 v220, v220
	v_rcp_f32_e32 v221, v221
	v_rcp_f32_e32 v222, v222
	v_rcp_f32_e32 v223, v223
	v_pk_mul_f32 v[100:101], v[100:101], v[220:221]
	v_pk_mul_f32 v[102:103], v[102:103], v[222:223]
	v_cvt_pk_bf16_f32 v100, v100, v101
	v_cvt_pk_bf16_f32 v101, v102, v103
	global_store_dwordx2 v[198:199], v[100:101], off offset:128
	v_mul_f32_e32 v216, v92, v174
	v_mul_f32_e32 v217, v94, v174
	v_mul_f32_e32 v218, v88, v174
	v_mul_f32_e32 v219, v90, v174
	v_mul_f32_e32 v92, v92, v93
	v_mul_f32_e32 v93, v94, v95
	v_mul_f32_e32 v94, v88, v89
	v_mul_f32_e32 v95, v90, v91
	v_exp_f32_e32 v216, v216
	v_exp_f32_e32 v217, v217
	v_exp_f32_e32 v218, v218
	v_exp_f32_e32 v219, v219
	v_pk_fma_f32 v[216:217], v[216:217], v[232:233], v[232:233] op_sel_hi:[1,0,0]
	v_pk_fma_f32 v[218:219], v[218:219], v[232:233], v[232:233] op_sel_hi:[1,0,0]
	v_rcp_f32_e32 v216, v216
	v_rcp_f32_e32 v217, v217
	v_rcp_f32_e32 v218, v218
	v_rcp_f32_e32 v219, v219
	v_pk_mul_f32 v[92:93], v[92:93], v[216:217]
	v_pk_mul_f32 v[94:95], v[94:95], v[218:219]
	v_cvt_pk_bf16_f32 v92, v92, v93
	v_cvt_pk_bf16_f32 v93, v94, v95
	global_store_dwordx2 v[200:201], v[92:93], off
	v_mul_f32_e32 v220, v84, v174
	v_mul_f32_e32 v221, v86, v174
	v_mul_f32_e32 v222, v80, v174
	v_mul_f32_e32 v223, v82, v174
	v_mul_f32_e32 v84, v84, v85
	v_mul_f32_e32 v85, v86, v87
	v_mul_f32_e32 v86, v80, v81
	v_mul_f32_e32 v87, v82, v83
	v_exp_f32_e32 v220, v220
	v_exp_f32_e32 v221, v221
	v_exp_f32_e32 v222, v222
	v_exp_f32_e32 v223, v223
	v_pk_fma_f32 v[220:221], v[220:221], v[232:233], v[232:233] op_sel_hi:[1,0,0]
	v_pk_fma_f32 v[222:223], v[222:223], v[232:233], v[232:233] op_sel_hi:[1,0,0]
	v_rcp_f32_e32 v220, v220
	v_rcp_f32_e32 v221, v221
	v_rcp_f32_e32 v222, v222
	v_rcp_f32_e32 v223, v223
	v_pk_mul_f32 v[84:85], v[84:85], v[220:221]
	v_pk_mul_f32 v[86:87], v[86:87], v[222:223]
	v_cvt_pk_bf16_f32 v84, v84, v85
	v_cvt_pk_bf16_f32 v85, v86, v87
	global_store_dwordx2 v[200:201], v[84:85], off offset:128
	v_mul_f32_e32 v216, v76, v175
	v_mul_f32_e32 v217, v78, v175
	v_mul_f32_e32 v218, v72, v175
	v_mul_f32_e32 v219, v74, v175
	v_mul_f32_e32 v76, v76, v77
	v_mul_f32_e32 v77, v78, v79
	v_mul_f32_e32 v78, v72, v73
	v_mul_f32_e32 v79, v74, v75
	v_exp_f32_e32 v216, v216
	v_exp_f32_e32 v217, v217
	v_exp_f32_e32 v218, v218
	v_exp_f32_e32 v219, v219
	v_pk_fma_f32 v[216:217], v[216:217], v[232:233], v[232:233] op_sel:[0,1,1] op_sel_hi:[1,1,1]
	v_pk_fma_f32 v[218:219], v[218:219], v[232:233], v[232:233] op_sel:[0,1,1] op_sel_hi:[1,1,1]
	v_rcp_f32_e32 v216, v216
	v_rcp_f32_e32 v217, v217
	v_rcp_f32_e32 v218, v218
	v_rcp_f32_e32 v219, v219
	v_pk_mul_f32 v[76:77], v[76:77], v[216:217]
	v_pk_mul_f32 v[78:79], v[78:79], v[218:219]
	v_cvt_pk_bf16_f32 v76, v76, v77
	v_cvt_pk_bf16_f32 v77, v78, v79
	global_store_dwordx2 v[202:203], v[76:77], off
	v_mul_f32_e32 v220, v68, v175
	v_mul_f32_e32 v221, v70, v175
	v_mul_f32_e32 v222, v64, v175
	v_mul_f32_e32 v223, v66, v175
	v_mul_f32_e32 v68, v68, v69
	v_mul_f32_e32 v69, v70, v71
	v_mul_f32_e32 v70, v64, v65
	v_mul_f32_e32 v71, v66, v67
	v_exp_f32_e32 v220, v220
	v_exp_f32_e32 v221, v221
	v_exp_f32_e32 v222, v222
	v_exp_f32_e32 v223, v223
	v_pk_fma_f32 v[220:221], v[220:221], v[232:233], v[232:233] op_sel:[0,1,1] op_sel_hi:[1,1,1]
	v_pk_fma_f32 v[222:223], v[222:223], v[232:233], v[232:233] op_sel:[0,1,1] op_sel_hi:[1,1,1]
	v_rcp_f32_e32 v220, v220
	v_rcp_f32_e32 v221, v221
	v_rcp_f32_e32 v222, v222
	v_rcp_f32_e32 v223, v223
	v_pk_mul_f32 v[68:69], v[68:69], v[220:221]
	v_pk_mul_f32 v[70:71], v[70:71], v[222:223]
	v_cvt_pk_bf16_f32 v68, v68, v69
	v_cvt_pk_bf16_f32 v69, v70, v71
	global_store_dwordx2 v[202:203], v[68:69], off offset:128
	v_mul_f32_e32 v216, v60, v176
	v_mul_f32_e32 v217, v62, v176
	v_mul_f32_e32 v218, v56, v176
	v_mul_f32_e32 v219, v58, v176
	v_mul_f32_e32 v60, v60, v61
	v_mul_f32_e32 v61, v62, v63
	v_mul_f32_e32 v62, v56, v57
	v_mul_f32_e32 v63, v58, v59
	v_exp_f32_e32 v216, v216
	v_exp_f32_e32 v217, v217
	v_exp_f32_e32 v218, v218
	v_exp_f32_e32 v219, v219
	v_pk_fma_f32 v[216:217], v[216:217], v[234:235], v[234:235] op_sel_hi:[1,0,0]
	v_pk_fma_f32 v[218:219], v[218:219], v[234:235], v[234:235] op_sel_hi:[1,0,0]
	v_rcp_f32_e32 v216, v216
	v_rcp_f32_e32 v217, v217
	v_rcp_f32_e32 v218, v218
	v_rcp_f32_e32 v219, v219
	v_pk_mul_f32 v[60:61], v[60:61], v[216:217]
	v_pk_mul_f32 v[62:63], v[62:63], v[218:219]
	v_cvt_pk_bf16_f32 v60, v60, v61
	v_cvt_pk_bf16_f32 v61, v62, v63
	global_store_dwordx2 v[204:205], v[60:61], off
	v_mul_f32_e32 v220, v52, v176
	v_mul_f32_e32 v221, v54, v176
	v_mul_f32_e32 v222, v48, v176
	v_mul_f32_e32 v223, v50, v176
	v_mul_f32_e32 v52, v52, v53
	v_mul_f32_e32 v53, v54, v55
	v_mul_f32_e32 v54, v48, v49
	v_mul_f32_e32 v55, v50, v51
	v_exp_f32_e32 v220, v220
	v_exp_f32_e32 v221, v221
	v_exp_f32_e32 v222, v222
	v_exp_f32_e32 v223, v223
; __device__ __forceinline__ unsigned cvt_pk_bf16(float lo, float hi) { return pk_bf16(lo, hi); }
; __device__ __forceinline__ float silu_f(float x) { return x * __builtin_amdgcn_rcpf(1.f + __builtin_amdgcn_exp2f(-x * L2E)); }
;     __device__ __forceinline__ void operator()(const f32x4 (&acc)[2][2][4][2], const Unit& u, int wr, int wc, int fr, int fq) const {
;         EPI_ROWS_BEGIN
;             const int hc = (u.pn * BM + colt) >> 1; const float r = 1.f / sqrtf(rstd[row] * (1.f / DM) + RMS_EPS);
;             const float h0 = silu_f(v0[0] * r) * (v0[1] * r), h1 = silu_f(v0[2] * r) * (v0[3] * r), h2 = silu_f(v1[0] * r) * (v1[1] * r), h3 = silu_f(v1[2] * r) * (v1[3] * r);
;             u32x2 w; w.x = cvt_pk_bf16(h0, h1); w.y = cvt_pk_bf16(h2, h3);
;             *(u32x2*)(hid + (size_t)row * HIDLD + hc) = w;
	v_pk_fma_f32 v[220:221], v[220:221], v[234:235], v[234:235] op_sel_hi:[1,0,0]
	v_pk_fma_f32 v[222:223], v[222:223], v[234:235], v[234:235] op_sel_hi:[1,0,0]
	v_rcp_f32_e32 v220, v220
	v_rcp_f32_e32 v221, v221
	v_rcp_f32_e32 v222, v222
	v_rcp_f32_e32 v223, v223
	v_pk_mul_f32 v[52:53], v[52:53], v[220:221]
	v_pk_mul_f32 v[54:55], v[54:55], v[222:223]
	v_cvt_pk_bf16_f32 v52, v52, v53
	v_cvt_pk_bf16_f32 v53, v54, v55
	global_store_dwordx2 v[204:205], v[52:53], off offset:128
	v_mul_f32_e32 v216, v44, v177
	v_mul_f32_e32 v217, v46, v177
	v_mul_f32_e32 v218, v40, v177
	v_mul_f32_e32 v219, v42, v177
	v_mul_f32_e32 v44, v44, v45
	v_mul_f32_e32 v45, v46, v47
	v_mul_f32_e32 v46, v40, v41
	v_mul_f32_e32 v47, v42, v43
	v_exp_f32_e32 v216, v216
	v_exp_f32_e32 v217, v217
	v_exp_f32_e32 v218, v218
	v_exp_f32_e32 v219, v219
	v_pk_fma_f32 v[216:217], v[216:217], v[234:235], v[234:235] op_sel:[0,1,1] op_sel_hi:[1,1,1]
	v_pk_fma_f32 v[218:219], v[218:219], v[234:235], v[234:235] op_sel:[0,1,1] op_sel_hi:[1,1,1]
	v_rcp_f32_e32 v216, v216
	v_rcp_f32_e32 v217, v217
	v_rcp_f32_e32 v218, v218
	v_rcp_f32_e32 v219, v219
	v_pk_mul_f32 v[44:45], v[44:45], v[216:217]
	v_pk_mul_f32 v[46:47], v[46:47], v[218:219]
	v_cvt_pk_bf16_f32 v44, v44, v45
	v_cvt_pk_bf16_f32 v45, v46, v47
	global_store_dwordx2 v[206:207], v[44:45], off
	v_mul_f32_e32 v220, v36, v177
	v_mul_f32_e32 v221, v38, v177
	v_mul_f32_e32 v222, v32, v177
	v_mul_f32_e32 v223, v34, v177
	v_mul_f32_e32 v36, v36, v37
	v_mul_f32_e32 v37, v38, v39
	v_mul_f32_e32 v38, v32, v33
	v_mul_f32_e32 v39, v34, v35
	v_exp_f32_e32 v220, v220
	v_exp_f32_e32 v221, v221
	v_exp_f32_e32 v222, v222
	v_exp_f32_e32 v223, v223
	v_pk_fma_f32 v[220:221], v[220:221], v[234:235], v[234:235] op_sel:[0,1,1] op_sel_hi:[1,1,1]
	v_pk_fma_f32 v[222:223], v[222:223], v[234:235], v[234:235] op_sel:[0,1,1] op_sel_hi:[1,1,1]
	v_rcp_f32_e32 v220, v220
	v_rcp_f32_e32 v221, v221
	v_rcp_f32_e32 v222, v222
	v_rcp_f32_e32 v223, v223
	v_pk_mul_f32 v[36:37], v[36:37], v[220:221]
	v_pk_mul_f32 v[38:39], v[38:39], v[222:223]
	v_cvt_pk_bf16_f32 v36, v36, v37
	v_cvt_pk_bf16_f32 v37, v38, v39
	global_store_dwordx2 v[206:207], v[36:37], off offset:128
	v_mul_f32_e32 v216, v28, v178
	v_mul_f32_e32 v217, v30, v178
	v_mul_f32_e32 v218, v24, v178
	v_mul_f32_e32 v219, v26, v178
	v_mul_f32_e32 v28, v28, v29
	v_mul_f32_e32 v29, v30, v31
	v_mul_f32_e32 v30, v24, v25
	v_mul_f32_e32 v31, v26, v27
	v_exp_f32_e32 v216, v216
	v_exp_f32_e32 v217, v217
	v_exp_f32_e32 v218, v218
	v_exp_f32_e32 v219, v219
	v_pk_fma_f32 v[216:217], v[216:217], v[236:237], v[236:237] op_sel_hi:[1,0,0]
	v_pk_fma_f32 v[218:219], v[218:219], v[236:237], v[236:237] op_sel_hi:[1,0,0]
	v_rcp_f32_e32 v216, v216
	v_rcp_f32_e32 v217, v217
	v_rcp_f32_e32 v218, v218
	v_rcp_f32_e32 v219, v219
	v_pk_mul_f32 v[28:29], v[28:29], v[216:217]
	v_pk_mul_f32 v[30:31], v[30:31], v[218:219]
	v_cvt_pk_bf16_f32 v28, v28, v29
	v_cvt_pk_bf16_f32 v29, v30, v31
	global_store_dwordx2 v[208:209], v[28:29], off
	v_mul_f32_e32 v220, v20, v178
	v_mul_f32_e32 v221, v22, v178
	v_mul_f32_e32 v222, v16, v178
	v_mul_f32_e32 v223, v18, v178
	v_mul_f32_e32 v20, v20, v21
	v_mul_f32_e32 v21, v22, v23
	v_mul_f32_e32 v22, v16, v17
	v_mul_f32_e32 v23, v18, v19
	v_exp_f32_e32 v220, v220
	v_exp_f32_e32 v221, v221
	v_exp_f32_e32 v222, v222
	v_exp_f32_e32 v223, v223
	v_pk_fma_f32 v[220:221], v[220:221], v[236:237], v[236:237] op_sel_hi:[1,0,0]
	v_pk_fma_f32 v[222:223], v[222:223], v[236:237], v[236:237] op_sel_hi:[1,0,0]
	v_rcp_f32_e32 v220, v220
	v_rcp_f32_e32 v221, v221
	v_rcp_f32_e32 v222, v222
	v_rcp_f32_e32 v223, v223
	v_pk_mul_f32 v[20:21], v[20:21], v[220:221]
	v_pk_mul_f32 v[22:23], v[22:23], v[222:223]
	v_cvt_pk_bf16_f32 v20, v20, v21
	v_cvt_pk_bf16_f32 v21, v22, v23
	global_store_dwordx2 v[208:209], v[20:21], off offset:128
	v_mul_f32_e32 v216, v12, v179
	v_mul_f32_e32 v217, v14, v179
	v_mul_f32_e32 v218, v8, v179
	v_mul_f32_e32 v219, v10, v179
	v_mul_f32_e32 v12, v12, v13
	v_mul_f32_e32 v13, v14, v15
	v_mul_f32_e32 v14, v8, v9
	v_mul_f32_e32 v15, v10, v11
	v_exp_f32_e32 v216, v216
	v_exp_f32_e32 v217, v217
	v_exp_f32_e32 v218, v218
	v_exp_f32_e32 v219, v219
	v_pk_fma_f32 v[216:217], v[216:217], v[236:237], v[236:237] op_sel:[0,1,1] op_sel_hi:[1,1,1]
	v_pk_fma_f32 v[218:219], v[218:219], v[236:237], v[236:237] op_sel:[0,1,1] op_sel_hi:[1,1,1]
	v_rcp_f32_e32 v216, v216
	v_rcp_f32_e32 v217, v217
	v_rcp_f32_e32 v218, v218
	v_rcp_f32_e32 v219, v219
	v_pk_mul_f32 v[12:13], v[12:13], v[216:217]
	v_pk_mul_f32 v[14:15], v[14:15], v[218:219]
	v_cvt_pk_bf16_f32 v12, v12, v13
	v_cvt_pk_bf16_f32 v13, v14, v15
	global_store_dwordx2 v[210:211], v[12:13], off
	v_mul_f32_e32 v220, v4, v179
	v_mul_f32_e32 v221, v6, v179
	v_mul_f32_e32 v222, v0, v179
	v_mul_f32_e32 v223, v2, v179
	v_mul_f32_e32 v4, v4, v5
	v_mul_f32_e32 v5, v6, v7
	v_mul_f32_e32 v6, v0, v1
	v_mul_f32_e32 v7, v2, v3
	v_exp_f32_e32 v220, v220
	v_exp_f32_e32 v221, v221
	v_exp_f32_e32 v222, v222
	v_exp_f32_e32 v223, v223
	v_pk_fma_f32 v[220:221], v[220:221], v[236:237], v[236:237] op_sel:[0,1,1] op_sel_hi:[1,1,1]
	v_pk_fma_f32 v[222:223], v[222:223], v[236:237], v[236:237] op_sel:[0,1,1] op_sel_hi:[1,1,1]
	v_rcp_f32_e32 v220, v220
	v_rcp_f32_e32 v221, v221
	v_rcp_f32_e32 v222, v222
	v_rcp_f32_e32 v223, v223
	v_pk_mul_f32 v[4:5], v[4:5], v[220:221]
	v_pk_mul_f32 v[6:7], v[6:7], v[222:223]
	v_cvt_pk_bf16_f32 v4, v4, v5
	v_cvt_pk_bf16_f32 v5, v6, v7
	global_store_dwordx2 v[210:211], v[4:5], off offset:128
	s_mov_b64 s[0:1], -1
	s_andn2_b64 vcc, exec, s[4:5]
	s_cbranch_vccnz .LBB0_1045
	s_andn2_b64 vcc, exec, s[8:9]
	s_cbranch_vccnz .LBB0_1044
	s_barrier
	s_branch .LBB0_1044
